# speedup vs baseline: 1.0148x; 1.0039x over previous
; __global__ void __launch_bounds__(512, 2) fwd_kernel(KP p) {
;     ...
;         for (int e = gt; e < 2 * NG * NP; e += NGT) {
;             const int d = e / (NG * NP), g = (e / NP) % NG, pp = e % NP;
;             const float lre = p.in[I_LRE][e], lim = p.in[I_LIM][e], dt = __expf(p.in[I_LDT][d * NG + g]);
;             const float a = lre * dt, bb = lim * dt;
;             float sn, cs; sincosf(bb, &sn, &cs); const float sh = sinf(0.5f * bb), em1 = expm1f(a);
;             const float nre = em1 * cs - 2.f * sh * sh, nim = (em1 + 1.f) * sn;
;             const float den = lre * lre + lim * lim; const float cre = (nre * lre + nim * lim) / den, cim = (nim * lre - nre * lim) / den;
;             const float* br = p.in[I_BRE] + ((size_t)g * NP + pp) * GC; const float* bi = p.in[I_BIM] + ((size_t)g * NP + pp) * GC;
;             for (int c = 0; c < GC; ++c) BB[(size_t)e * GC + c] = (f32x2){cre * br[c] - cim * bi[c], cre * bi[c] + cim * br[c]};
;         }
.LBB0_106:
	s_or_b64 exec, exec, s[0:1]
	v_mul_f32_e32 v24, v21, v21
	v_fmamk_f32 v25, v24, 0xb94c1982, v10
	v_fmaak_f32 v25, v24, v25, 0xbe2aaa9d
	v_mul_f32_e32 v25, v24, v25
	v_fmac_f32_e32 v21, v21, v25
	v_fmamk_f32 v25, v24, 0x37d75334, v11
	v_fmaak_f32 v25, v24, v25, 0x3d2aabf7
	v_fmaak_f32 v25, v24, v25, 0xbf000004
	v_fma_f32 v24, v24, v25, 1.0
	v_lshlrev_b32_e32 v25, 30, v22
	v_and_b32_e32 v22, 1, v22
	v_cmp_eq_u32_e32 vcc, 0, v22
	v_lshlrev_b32_e32 v7, 6, v7
	v_mul_f32_e32 v28, v23, v23
	v_cndmask_b32_e32 v22, v24, v21, vcc
	v_xor_b32_e32 v21, 0x80000000, v21
	v_cndmask_b32_e32 v21, v21, v24, vcc
	v_sub_u32_e32 v24, v4, v7
	v_fmamk_f32 v7, v28, 0xb94c1982, v10
	v_fmaak_f32 v7, v28, v7, 0xbe2aaa9d
	v_mul_f32_e32 v7, v28, v7
	v_fmac_f32_e32 v23, v23, v7
	v_ashrrev_i32_e32 v7, 31, v6
	v_readlane_b32 s72, v254, 26
	v_and_b32_e32 v26, 0x80000000, v25
	v_bitop3_b32 v21, v21, v25, s37 bitop3:0x78
	v_ashrrev_i32_e32 v25, 31, v24
	v_lshlrev_b64 v[6:7], 10, v[6:7]
	v_readlane_b32 s73, v254, 27
	v_readlane_b32 s74, v254, 28
	v_readlane_b32 s75, v254, 29
	v_readlane_b32 s76, v254, 30
	v_readlane_b32 s77, v254, 31
	v_readlane_b32 s78, v254, 32
	v_readlane_b32 s79, v254, 33
	v_xor_b32_e32 v18, v18, v9
	v_lshl_add_u64 v[6:7], v[24:25], 4, v[6:7]
	v_readlane_b32 s64, v254, 53
	v_xor_b32_e32 v18, v18, v22
	v_cmp_class_f32_e64 vcc, v9, s38
	s_waitcnt vmcnt(0)
	v_mul_f32_e32 v27, v2, v8
	v_lshlrev_b64 v[8:9], 2, v[6:7]
	v_readlane_b32 s86, v254, 40
	v_readlane_b32 s87, v254, 41
	v_readlane_b32 s65, v254, 54
	v_xor_b32_e32 v18, v18, v26
	v_lshl_add_u64 v[6:7], s[86:87], 0, v[8:9]
	v_lshl_add_u64 v[8:9], s[64:65], 0, v[8:9]
	v_cndmask_b32_e32 v26, v15, v18, vcc
	global_load_dwordx4 v[32:35], v[8:9], off
	global_load_dwordx4 v[36:39], v[8:9], off offset:16
	global_load_dwordx4 v[40:43], v[8:9], off offset:32
	global_load_dwordx4 v[44:47], v[8:9], off offset:48
	global_load_dwordx4 v[48:51], v[6:7], off
	global_load_dwordx4 v[52:55], v[6:7], off offset:16
	global_load_dwordx4 v[56:59], v[6:7], off offset:32
	global_load_dwordx4 v[60:63], v[6:7], off offset:48
	v_fmamk_f32 v24, v28, 0x37d75334, v11
	v_fmaak_f32 v24, v28, v24, 0x3d2aabf7
	v_fmaak_f32 v24, v28, v24, 0xbf000004
	v_and_b32_e32 v25, 1, v0
	v_cndmask_b32_e32 v21, v15, v21, vcc
	v_fma_f32 v24, v28, v24, 1.0
	v_cmp_eq_u32_e32 vcc, 0, v25
	v_lshlrev_b32_e32 v0, 30, v0
	v_xor_b32_e32 v20, v20, v19
	v_cndmask_b32_e32 v23, v24, v23, vcc
	v_cmp_class_f32_e64 vcc, v19, s38
	v_mul_f32_e32 v19, 0x3fb8aa3b, v27
	v_and_b32_e32 v0, 0x80000000, v0
	v_rndne_f32_e32 v19, v19
	v_xor_b32_e32 v0, v20, v0
	v_fmamk_f32 v20, v19, 0xbf317218, v27
	v_fmac_f32_e32 v20, 0x3102e308, v19
	v_xor_b32_e32 v0, v0, v23
	v_fmamk_f32 v23, v20, 0x395133b1, v12
	v_fmaak_f32 v23, v20, v23, 0x3c0887f9
	v_fmaak_f32 v23, v20, v23, 0x3d2aaa81
	v_cvt_i32_f32_e32 v24, v19
	v_fmaak_f32 v23, v20, v23, 0x3e2aaaab
	v_fma_f32 v23, v20, v23, 0.5
	v_mul_f32_e32 v23, v20, v23
	v_cndmask_b32_e32 v0, v15, v0, vcc
	v_fmac_f32_e32 v20, v20, v23
	v_ldexp_f32 v23, 1.0, v24
	v_cmp_eq_f32_e32 vcc, s39, v19
	v_pk_mul_f32 v[24:25], v[2:3], v[2:3]
	v_lshlrev_b64 v[30:31], 7, v[4:5]
	v_cndmask_b32_e32 v19, v23, v16, vcc
	v_add_f32_e32 v23, -1.0, v19
	v_fmac_f32_e32 v23, v19, v20
	v_add_f32_e32 v19, v23, v23
	v_cndmask_b32_e32 v19, v23, v19, vcc
	v_cmp_nlt_f32_e32 vcc, s43, v27
	v_add_f32_e32 v20, v0, v0
	v_mul_f32_e32 v0, v0, v20
	v_cndmask_b32_e32 v19, v17, v19, vcc
	v_cmp_ngt_f32_e32 vcc, s48, v27
	v_pk_add_f32 v[24:25], v[24:25], v[24:25] op_sel:[0,1] op_sel_hi:[0,1]
	v_lshl_add_u64 v[30:31], s[22:23], 0, v[30:31]
	v_cndmask_b32_e32 v19, -1.0, v19, vcc
	v_fma_f32 v20, v19, v21, -v0
	v_add_f32_e32 v0, 1.0, v19
	v_mul_f32_e32 v21, v0, v26
	v_mov_b32_e32 v0, v3
	v_pk_mul_f32 v[26:27], v[0:1], v[20:21] op_sel:[0,1] op_sel_hi:[0,0]
	v_pk_fma_f32 v[28:29], v[2:3], v[20:21], v[26:27] op_sel_hi:[0,1,1] neg_lo:[0,0,1] neg_hi:[0,0,1]
	v_div_scale_f32 v0, s[0:1], v25, v25, v29
	v_rcp_f32_e32 v19, v0
	v_pk_fma_f32 v[2:3], v[2:3], v[20:21], v[26:27]
	v_add_u32_e32 v4, s42, v4
	v_readlane_b32 s80, v254, 34
	v_fma_f32 v3, -v0, v19, 1.0
	v_fmac_f32_e32 v19, v3, v19
	v_div_scale_f32 v3, vcc, v29, v25, v29
	v_mul_f32_e32 v5, v3, v19
	v_fma_f32 v20, -v0, v5, v3
	v_fmac_f32_e32 v5, v20, v19
	v_div_scale_f32 v20, s[0:1], v24, v24, v2
	v_rcp_f32_e32 v21, v20
	v_fma_f32 v0, -v0, v5, v3
	v_div_fmas_f32 v0, v0, v19, v5
	v_div_fixup_f32 v3, v0, v25, v29
	v_fma_f32 v0, -v20, v21, 1.0
	v_fmac_f32_e32 v21, v0, v21
	v_div_scale_f32 v0, vcc, v2, v24, v2
	v_mul_f32_e32 v5, v0, v21
	v_fma_f32 v19, -v20, v5, v0
	v_fmac_f32_e32 v5, v19, v21
	v_fma_f32 v0, -v20, v5, v0
	v_div_fmas_f32 v0, v0, v21, v5
	v_div_fixup_f32 v2, v0, v24, v2
	s_waitcnt vmcnt(0)
; __global__ void __launch_bounds__(512, 2) fwd_kernel(KP p) {
;     ...
;             float sn, cs; sincosf(bb, &sn, &cs); const float sh = sinf(0.5f * bb), em1 = expm1f(a);
;             const float nre = em1 * cs - 2.f * sh * sh, nim = (em1 + 1.f) * sn;
;             const float den = lre * lre + lim * lim; const float cre = (nre * lre + nim * lim) / den, cim = (nim * lre - nre * lim) / den;
;             const float* br = p.in[I_BRE] + ((size_t)g * NP + pp) * GC; const float* bi = p.in[I_BIM] + ((size_t)g * NP + pp) * GC;
;             for (int c = 0; c < GC; ++c) BB[(size_t)e * GC + c] = (f32x2){cre * br[c] - cim * bi[c], cre * bi[c] + cim * br[c]};
;         }
	v_mul_f32_e32 v96, v3, v32
	v_mul_f32_e32 v97, v2, v32
	v_fma_f32 v64, v2, v48, -v96
	v_fma_f32 v65, v3, v48, v97
	v_mul_f32_e32 v96, v3, v33
	v_mul_f32_e32 v97, v2, v33
	v_fma_f32 v66, v2, v49, -v96
	v_fma_f32 v67, v3, v49, v97
	v_mul_f32_e32 v96, v3, v34
	v_mul_f32_e32 v97, v2, v34
	v_fma_f32 v68, v2, v50, -v96
	v_fma_f32 v69, v3, v50, v97
	v_mul_f32_e32 v96, v3, v35
	v_mul_f32_e32 v97, v2, v35
	v_fma_f32 v70, v2, v51, -v96
	v_fma_f32 v71, v3, v51, v97
	v_mul_f32_e32 v96, v3, v36
	v_mul_f32_e32 v97, v2, v36
	v_fma_f32 v72, v2, v52, -v96
	v_fma_f32 v73, v3, v52, v97
	v_mul_f32_e32 v96, v3, v37
	v_mul_f32_e32 v97, v2, v37
	v_fma_f32 v74, v2, v53, -v96
	v_fma_f32 v75, v3, v53, v97
	v_mul_f32_e32 v96, v3, v38
	v_mul_f32_e32 v97, v2, v38
	v_fma_f32 v76, v2, v54, -v96
	v_fma_f32 v77, v3, v54, v97
	v_mul_f32_e32 v96, v3, v39
	v_mul_f32_e32 v97, v2, v39
	v_fma_f32 v78, v2, v55, -v96
	v_fma_f32 v79, v3, v55, v97
	v_mul_f32_e32 v96, v3, v40
	v_mul_f32_e32 v97, v2, v40
	v_fma_f32 v80, v2, v56, -v96
	v_fma_f32 v81, v3, v56, v97
	v_mul_f32_e32 v96, v3, v41
	v_mul_f32_e32 v97, v2, v41
	v_fma_f32 v82, v2, v57, -v96
	v_fma_f32 v83, v3, v57, v97
	v_mul_f32_e32 v96, v3, v42
	v_mul_f32_e32 v97, v2, v42
	v_fma_f32 v84, v2, v58, -v96
	v_fma_f32 v85, v3, v58, v97
	v_mul_f32_e32 v96, v3, v43
	v_mul_f32_e32 v97, v2, v43
	v_fma_f32 v86, v2, v59, -v96
	v_fma_f32 v87, v3, v59, v97
	v_mul_f32_e32 v96, v3, v44
	v_mul_f32_e32 v97, v2, v44
	v_fma_f32 v88, v2, v60, -v96
	v_fma_f32 v89, v3, v60, v97
	v_mul_f32_e32 v96, v3, v45
	v_mul_f32_e32 v97, v2, v45
	v_fma_f32 v90, v2, v61, -v96
	v_fma_f32 v91, v3, v61, v97
	v_mul_f32_e32 v96, v3, v46
	v_mul_f32_e32 v97, v2, v46
	v_fma_f32 v92, v2, v62, -v96
	v_fma_f32 v93, v3, v62, v97
	v_mul_f32_e32 v96, v3, v47
	v_mul_f32_e32 v97, v2, v47
	v_fma_f32 v94, v2, v63, -v96
	v_fma_f32 v95, v3, v63, v97
	v_cmp_lt_i32_e32 vcc, s49, v4
	v_readlane_b32 s81, v254, 35
	v_readlane_b32 s82, v254, 36
	v_readlane_b32 s83, v254, 37
	v_readlane_b32 s84, v254, 38
	v_readlane_b32 s85, v254, 39
	s_or_b64 s[24:25], vcc, s[24:25]
	v_readlane_b32 s66, v254, 55
	v_readlane_b32 s67, v254, 56
	v_readlane_b32 s68, v254, 57
	v_readlane_b32 s69, v254, 58
	v_readlane_b32 s70, v254, 59
	v_readlane_b32 s71, v254, 60
	v_readlane_b32 s72, v254, 61
	v_readlane_b32 s73, v254, 62
	v_readlane_b32 s74, v254, 63
	v_readlane_b32 s75, v253, 0
	v_readlane_b32 s76, v253, 1
	v_readlane_b32 s77, v253, 2
	v_readlane_b32 s78, v253, 3
	v_readlane_b32 s79, v253, 4
	global_store_dwordx4 v[30:31], v[64:67], off
	global_store_dwordx4 v[30:31], v[68:71], off offset:16
	global_store_dwordx4 v[30:31], v[72:75], off offset:32
	global_store_dwordx4 v[30:31], v[76:79], off offset:48
	global_store_dwordx4 v[30:31], v[80:83], off offset:64
	global_store_dwordx4 v[30:31], v[84:87], off offset:80
	global_store_dwordx4 v[30:31], v[88:91], off offset:96
	global_store_dwordx4 v[30:31], v[92:95], off offset:112
	s_andn2_b64 exec, exec, s[24:25]
	s_cbranch_execz .LBB0_115

; __global__ void __launch_bounds__(512, 2) fwd_kernel(KP p) {
;     ...
;         for (int e = bt_first + tid; e < NG * 512 * 96; e += bt_stride) {
;             const int kc = e % 96, row = (e / 96) & 511, g = e / (96 * 512); const int t = row >> 4, c = row & 15, k0 = kc * 8; float o[8];
;             if (k0 < 512) { const int j = k0 >> 4, c0 = k0 & 15;
; #pragma unroll
;                 for (int q = 0; q < 8; ++q) { float v = 0.f; if (t >= j) v += KF[(((size_t)(0 * NG + g) * CT + (t - j)) * 16 + c) * 16 + c0 + q]; if (j >= t) v += KF[(((size_t)(1 * NG + g) * CT + (j - t)) * 16 + c) * 16 + c0 + q]; o[q] = v; }
.LBB0_611:
	s_andn2_saveexec_b64 s[20:21], s[20:21]
	s_cbranch_execz .LBB0_608
	v_ashrrev_i32_e32 v7, 1, v12
	v_sub_u32_e32 v4, v20, v7
	v_max_i32_e32 v4, 0, v4
	v_lshlrev_b64 v[10:11], 9, v[8:9]
	v_lshl_add_u64 v[12:13], v[4:5], 4, v[10:11]
	v_or_b32_e32 v12, v12, v18
	v_and_b32_e32 v3, 8, v6
	v_lshlrev_b64 v[12:13], 6, v[12:13]
	v_lshl_add_u64 v[12:13], s[48:49], 0, v[12:13]
	v_lshlrev_b32_e32 v4, 2, v3
	v_cmp_ge_i32_e32 vcc, v20, v7
	v_lshl_add_u64 v[12:13], v[12:13], 0, v[4:5]
	global_load_dwordx4 v[64:67], v[12:13], off
	global_load_dwordx4 v[68:71], v[12:13], off offset:16
	v_lshlrev_b64 v[8:9], 9, v[8:9]
	v_sub_u32_e32 v14, v7, v20
	v_max_i32_e32 v14, 0, v14
	v_mov_b32_e32 v15, v5
	v_lshl_add_u64 v[8:9], v[14:15], 4, v[8:9]
	v_or_b32_e32 v8, v8, v18
	v_lshlrev_b64 v[8:9], 6, v[8:9]
	v_lshl_add_u64 v[8:9], s[48:49], 0, v[8:9]
	v_lshl_add_u64 v[8:9], v[8:9], 0, v[4:5]
	s_mov_b64 s[18:19], 0x200000
	v_cmp_ge_i32_e64 s[34:35], v7, v20
	v_lshl_add_u64 v[8:9], v[8:9], 0, s[18:19]
	global_load_dwordx4 v[72:75], v[8:9], off
	global_load_dwordx4 v[76:79], v[8:9], off offset:16
	s_waitcnt vmcnt(0)
	v_cndmask_b32_e32 v80, 0, v64, vcc
	v_cndmask_b32_e64 v81, 0, v72, s[34:35]
	v_add_f32_e32 v80, 0, v80
	v_add_f32_e32 v3, v80, v81
	v_cndmask_b32_e32 v80, 0, v65, vcc
	v_cndmask_b32_e64 v81, 0, v73, s[34:35]
	v_add_f32_e32 v80, 0, v80
	v_add_f32_e32 v4, v80, v81
	v_cndmask_b32_e32 v80, 0, v66, vcc
	v_cndmask_b32_e64 v81, 0, v74, s[34:35]
	v_add_f32_e32 v80, 0, v80
	v_add_f32_e32 v7, v80, v81
	v_cndmask_b32_e32 v80, 0, v67, vcc
	v_cndmask_b32_e64 v81, 0, v75, s[34:35]
	v_add_f32_e32 v80, 0, v80
	v_add_f32_e32 v14, v80, v81
	v_cndmask_b32_e32 v80, 0, v68, vcc
	v_cndmask_b32_e64 v81, 0, v76, s[34:35]
	v_add_f32_e32 v80, 0, v80
	v_add_f32_e32 v15, v80, v81
	v_cndmask_b32_e32 v80, 0, v69, vcc
	v_cndmask_b32_e64 v81, 0, v77, s[34:35]
	v_add_f32_e32 v80, 0, v80
	v_add_f32_e32 v16, v80, v81
	v_cndmask_b32_e32 v80, 0, v70, vcc
	v_cndmask_b32_e64 v81, 0, v78, s[34:35]
	v_add_f32_e32 v80, 0, v80
	v_add_f32_e32 v17, v80, v81
	v_cndmask_b32_e32 v80, 0, v71, vcc
	v_cndmask_b32_e64 v81, 0, v79, s[34:35]
	v_add_f32_e32 v80, 0, v80
	v_add_f32_e32 v19, v80, v81
	s_branch .LBB0_608
